# window branch: V tile loads issued inside the QK MFMA shadow (on top of the pass-2 variant)
# baseline (speedup 1.0000x reference)
; __device__ __forceinline__ void nsa_unit(const Params& p, int bg, int jq, LAS unsigned char* lds, int wave, int lane, bool build_lut) {
;     ...
;         load_k(kn, kwb + (size_t)(32 * T0) * 64, lane);
;         for (int T = T0; T <= T1; ++T) {
; #pragma unroll
;             for (int ks = 0; ks < 4; ++ks) kf[ks] = kn[ks];
;             load_v(vf, vwT + (size_t)T * 2048, lane);
;             if (T < T1) load_k(kn, kwb + (size_t)(32 * (T + 1)) * 64, lane);
;             const int base = 32 * T;
;             f32x16 s = qk_tile(kf, qf);
;             if (((tq0 - base - 31) >= 128) && ((tq0 + 7 - base) < 512)) online_step<true>(s, lutfar, true, m, l, o0, o1, vf);
.LBB0_1282:
	s_cmp_ge_i32 s4, s12
	s_cselect_b64 s[8:9], -1, 0
.LBB0_1284:
	s_waitcnt lgkmcnt(0)
	v_mfma_f32_32x32x16_bf16 v[48:63], v[2:5], v[140:143], 0
	global_load_dwordx4 v[160:163], v[220:221], off offset:-2048
	global_load_dwordx4 v[152:155], v[220:221], off offset:-1024
	global_load_dwordx4 v[156:159], v[220:221], off
	global_load_dwordx4 v[148:151], v[220:221], off offset:1024
	s_add_i32 s5, s13, -7
	s_cmpk_gt_i32 s5, 0x9e
	s_cselect_b64 s[10:11], -1, 0
	s_cmpk_lt_i32 s13, 0x200
	s_cselect_b64 s[16:17], -1, 0
	s_and_b64 s[16:17], s[10:11], s[16:17]
	s_mov_b64 s[10:11], -1
	v_mfma_f32_32x32x16_bf16 v[48:63], v[6:9], v[136:139], v[48:63]
	s_andn2_b64 vcc, exec, s[16:17]
	v_mfma_f32_32x32x16_bf16 v[48:63], v[10:13], v[132:135], v[48:63]
	v_mfma_f32_32x32x16_bf16 v[48:63], v[144:147], v[128:131], v[48:63]
	s_cmp_ge_i32 s4, s12
	s_cbranch_scc1 .Lw_noload
	s_ashr_i32 s7, s6, 31
	s_lshl_b64 s[100:101], s[6:7], 7
	v_lshl_add_u64 v[238:239], v[14:15], 0, s[100:101]
	global_load_dwordx4 v[2:5], v[238:239], off
	global_load_dwordx4 v[6:9], v[238:239], off offset:1024
	global_load_dwordx4 v[10:13], v[238:239], off offset:2048
	global_load_dwordx4 v[144:147], v[238:239], off offset:3072
